# speedup vs baseline: 1.0205x; 1.0142x over previous
; __device__ __forceinline__ float b2f(u16 b) { return __uint_as_float(((unsigned)b) << 16); }
; __device__ __forceinline__ float sigmoidf_(float x) { return __builtin_amdgcn_rcpf(1.f + __builtin_amdgcn_exp2f(-1.4426950408889634f * x)); }
; #define MFMA16(a, b, c) __builtin_amdgcn_mfma_f32_16x16x32_bf16(a, b, c, 0, 0, 0)
; __device__ __forceinline__ void vmix_phase(u16* V, const u16* VF, const u16* vmid, const u16* v2T, const float* v0) {
;   int tid_ = threadIdx.x; asm volatile("" : "+v"(tid_));
;   int wv = tid_ >> 6, lane = tid_ & 63, fr = lane & 15, fq = lane >> 4;
;   for (int it = blockIdx.x; it < NTOK / 16; it += gridDim.x) {
;     int tok0 = it * 16;
;     bf16x8 a = ld8(vmid + (size_t)(tok0 + fr) * 32 + fq * 8);
;     _Pragma("unroll") for (int n = 0; n < 8; ++n) {
;       int ch = wv * 128 + n * 16 + fr;
;       bf16x8 b = ld8(v2T + (size_t)ch * 32 + fq * 8);
;       f32x4 acc = {0.f, 0.f, 0.f, 0.f};
;       acc = MFMA16(a, b, acc);
;       float v0c = v0[ch];
;       _Pragma("unroll") for (int j = 0; j < 4; ++j) {
;         size_t idx = (size_t)(tok0 + fq * 4 + j) * CM + ch;
;         float v = b2f(V[idx]), vf = b2f(VF[idx]);
;         V[idx] = f2b(v + (vf - v) * sigmoidf_(v0c + acc[j]));
;       }
;     }
.LBB0_2638:
	s_and_b64 s[0:1], s[12:13], exec
	v_readlane_b32 s0, v246, 34
	v_readlane_b32 s1, v246, 35
	s_cselect_b32 s5, s97, s31
	s_cselect_b32 s4, s96, s30
	s_and_b64 vcc, exec, s[0:1]
	v_readlane_b32 s0, v247, 37
	v_readlane_b32 s1, v247, 38
	s_nop 1
	v_cndmask_b32_e64 v0, 0, 1, s[0:1]
	v_cmp_ne_u32_e64 s[16:17], 1, v0
	s_cbranch_vccz .LBB0_2681
	v_readlane_b32 s60, v248, 2
	v_readlane_b32 s61, v248, 3
	v_readlane_b32 s62, v248, 4
	v_readlane_b32 s63, v248, 5
	v_readlane_b32 s64, v248, 6
	v_readlane_b32 s65, v248, 7
	v_readlane_b32 s66, v248, 8
	v_readlane_b32 s67, v248, 9
	v_readlane_b32 s68, v248, 10
	v_readlane_b32 s69, v248, 11
	v_readlane_b32 s70, v248, 12
	v_readlane_b32 s71, v248, 13
	v_readlane_b32 s72, v248, 14
	v_readlane_b32 s73, v248, 15
	v_readlane_b32 s74, v248, 16
	v_readlane_b32 s75, v248, 17
	s_mov_b64 s[6:7], s[74:75]
	s_mov_b64 s[0:1], s[74:75]
	v_readlane_b32 s60, v248, 36
	v_readlane_b32 s72, v248, 48
	v_readlane_b32 s73, v248, 49
	s_mov_b64 s[8:9], s[72:73]
	v_mov_b32_e32 v0, v131
	s_and_b64 vcc, exec, s[16:17]
	v_readlane_b32 s10, v246, 17
	v_readlane_b32 s61, v248, 37
	v_readlane_b32 s62, v248, 38
	v_readlane_b32 s63, v248, 39
	v_readlane_b32 s64, v248, 40
	v_readlane_b32 s65, v248, 41
	v_readlane_b32 s66, v248, 42
	v_readlane_b32 s67, v248, 43
	v_readlane_b32 s68, v248, 44
	v_readlane_b32 s69, v248, 45
	v_readlane_b32 s70, v248, 46
	v_readlane_b32 s71, v248, 47
	v_readlane_b32 s74, v248, 50
	v_readlane_b32 s75, v248, 51
	s_cbranch_vccnz .LBB0_2642
	v_and_b32_e32 v42, 15, v0
	v_lshlrev_b32_e32 v1, 1, v0
	s_movk_i32 s3, 0xff80
	v_and_or_b32 v8, v1, s3, v42
	v_ashrrev_i32_e32 v9, 31, v8
	v_lshl_add_u64 v[2:3], v[8:9], 2, s[8:9]
	global_load_dword v43, v[2:3], off
	global_load_dword v44, v[2:3], off offset:64
	global_load_dword v45, v[2:3], off offset:128
	global_load_dword v46, v[2:3], off offset:192
	global_load_dword v47, v[2:3], off offset:256
	global_load_dword v48, v[2:3], off offset:320
	global_load_dword v49, v[2:3], off offset:384
	global_load_dword v50, v[2:3], off offset:448
	v_bfe_u32 v2, v0, 4, 2
	v_lshlrev_b32_e32 v128, 4, v2
	v_lshl_add_u64 v[0:1], s[6:7], 0, v[128:129]
	s_mov_b64 s[6:7], 0x34e00000
	v_lshl_add_u64 v[10:11], v[0:1], 0, s[6:7]
	v_lshl_add_u64 v[0:1], s[0:1], 0, v[128:129]
	s_mov_b64 s[0:1], 0x3f4d0000
	v_lshl_add_u64 v[0:1], v[0:1], 0, s[0:1]
	v_lshlrev_b32_e32 v51, 2, v2
	v_lshlrev_b64 v[2:3], 6, v[8:9]
	v_lshl_add_u64 v[12:13], v[0:1], 0, v[2:3]
	v_or_b32_e32 v2, 16, v8
	v_ashrrev_i32_e32 v3, 31, v2
	v_lshlrev_b64 v[2:3], 6, v[2:3]
	v_lshl_add_u64 v[14:15], v[0:1], 0, v[2:3]
	v_or_b32_e32 v2, 32, v8
	v_ashrrev_i32_e32 v3, 31, v2
	v_lshlrev_b64 v[2:3], 6, v[2:3]
	v_lshl_add_u64 v[16:17], v[0:1], 0, v[2:3]
	v_or_b32_e32 v2, 48, v8
	v_ashrrev_i32_e32 v3, 31, v2
	v_lshlrev_b64 v[2:3], 6, v[2:3]
	v_lshl_add_u64 v[18:19], v[0:1], 0, v[2:3]
	v_or_b32_e32 v2, 64, v8
	v_ashrrev_i32_e32 v3, 31, v2
	v_lshlrev_b64 v[2:3], 6, v[2:3]
	v_lshl_add_u64 v[20:21], v[0:1], 0, v[2:3]
	v_or_b32_e32 v2, 0x50, v8
	v_ashrrev_i32_e32 v3, 31, v2
	v_lshlrev_b64 v[2:3], 6, v[2:3]
	v_lshl_add_u64 v[22:23], v[0:1], 0, v[2:3]
	v_or_b32_e32 v2, 0x60, v8
	v_ashrrev_i32_e32 v3, 31, v2
	v_lshlrev_b64 v[2:3], 6, v[2:3]
	v_lshl_add_u64 v[24:25], v[0:1], 0, v[2:3]
	v_or_b32_e32 v2, 0x70, v8
	v_ashrrev_i32_e32 v3, 31, v2
	v_lshlrev_b64 v[2:3], 6, v[2:3]
	v_lshl_add_u64 v[26:27], v[0:1], 0, v[2:3]
	v_readlane_b32 s0, v247, 32
	s_mov_b32 s1, s92
	global_load_dwordx4 v[56:59], v[12:13], off
	global_load_dwordx4 v[60:63], v[14:15], off
	global_load_dwordx4 v[64:67], v[16:17], off
	global_load_dwordx4 v[68:71], v[18:19], off
	global_load_dwordx4 v[72:75], v[20:21], off
	global_load_dwordx4 v[76:79], v[22:23], off
	global_load_dwordx4 v[80:83], v[24:25], off
	global_load_dwordx4 v[84:87], v[26:27], off
	s_waitcnt vmcnt(0)
.LBB0_2641:
	s_nop 0
	v_add_u32_e32 v0, s0, v42
	v_ashrrev_i32_e32 v1, 31, v0
	v_lshlrev_b64 v[0:1], 6, v[0:1]
	v_lshl_add_u64 v[0:1], v[10:11], 0, v[0:1]
	global_load_dwordx4 v[0:3], v[0:1], off
	v_add_u32_e32 v38, s0, v51
	s_add_i32 s1, s1, s76
	v_ashrrev_i32_e32 v39, 31, v38
	v_lshlrev_b64 v[4:5], 10, v[38:39]
	v_lshl_add_u64 v[4:5], v[4:5], 0, v[8:9]
	v_lshlrev_b64 v[4:5], 1, v[4:5]
	v_lshl_add_u64 v[132:133], s[4:5], 0, v[4:5]
	v_lshl_add_u64 v[134:135], s[96:97], 0, v[4:5]
	v_add_u32_e32 v4, 1, v38
	v_ashrrev_i32_e32 v5, 31, v4
	v_lshlrev_b64 v[4:5], 10, v[4:5]
	v_lshl_add_u64 v[4:5], v[4:5], 0, v[8:9]
	v_lshlrev_b64 v[4:5], 1, v[4:5]
	v_lshl_add_u64 v[136:137], s[4:5], 0, v[4:5]
	v_lshl_add_u64 v[138:139], s[96:97], 0, v[4:5]
	v_add_u32_e32 v4, 2, v38
	v_ashrrev_i32_e32 v5, 31, v4
	v_lshlrev_b64 v[4:5], 10, v[4:5]
	v_lshl_add_u64 v[4:5], v[4:5], 0, v[8:9]
	v_lshlrev_b64 v[4:5], 1, v[4:5]
	v_lshl_add_u64 v[140:141], s[4:5], 0, v[4:5]
	v_lshl_add_u64 v[142:143], s[96:97], 0, v[4:5]
	v_add_u32_e32 v4, 3, v38
	v_ashrrev_i32_e32 v5, 31, v4
	v_lshlrev_b64 v[4:5], 10, v[4:5]
	v_lshl_add_u64 v[4:5], v[4:5], 0, v[8:9]
	v_lshlrev_b64 v[4:5], 1, v[4:5]
	v_lshl_add_u64 v[144:145], s[4:5], 0, v[4:5]
	v_lshl_add_u64 v[146:147], s[96:97], 0, v[4:5]
	global_load_ushort v194, v[132:133], off
	global_load_ushort v88, v[134:135], off
	global_load_ushort v195, v[136:137], off
	global_load_ushort v89, v[138:139], off
	global_load_ushort v196, v[140:141], off
	global_load_ushort v90, v[142:143], off
	global_load_ushort v197, v[144:145], off
	global_load_ushort v91, v[146:147], off
	global_load_ushort v198, v[132:133], off offset:32
	global_load_ushort v92, v[134:135], off offset:32
	global_load_ushort v199, v[136:137], off offset:32
	global_load_ushort v93, v[138:139], off offset:32
	global_load_ushort v200, v[140:141], off offset:32
; __device__ __forceinline__ float b2f(u16 b) { return __uint_as_float(((unsigned)b) << 16); }
; __device__ __forceinline__ float sigmoidf_(float x) { return __builtin_amdgcn_rcpf(1.f + __builtin_amdgcn_exp2f(-1.4426950408889634f * x)); }
; #define MFMA16(a, b, c) __builtin_amdgcn_mfma_f32_16x16x32_bf16(a, b, c, 0, 0, 0)
; __device__ __forceinline__ void vmix_phase(u16* V, const u16* VF, const u16* vmid, const u16* v2T, const float* v0) {
;     ...
;     bf16x8 a = ld8(vmid + (size_t)(tok0 + fr) * 32 + fq * 8);
;     _Pragma("unroll") for (int n = 0; n < 8; ++n) {
;       int ch = wv * 128 + n * 16 + fr;
;       bf16x8 b = ld8(v2T + (size_t)ch * 32 + fq * 8);
;       f32x4 acc = {0.f, 0.f, 0.f, 0.f};
;       acc = MFMA16(a, b, acc);
;       float v0c = v0[ch];
;       _Pragma("unroll") for (int j = 0; j < 4; ++j) {
;         size_t idx = (size_t)(tok0 + fq * 4 + j) * CM + ch;
;         float v = b2f(V[idx]), vf = b2f(VF[idx]);
;         V[idx] = f2b(v + (vf - v) * sigmoidf_(v0c + acc[j]));
;       }
	global_load_ushort v94, v[142:143], off offset:32
	global_load_ushort v201, v[144:145], off offset:32
	global_load_ushort v95, v[146:147], off offset:32
	global_load_ushort v202, v[132:133], off offset:64
	global_load_ushort v96, v[134:135], off offset:64
	global_load_ushort v203, v[136:137], off offset:64
	global_load_ushort v97, v[138:139], off offset:64
	global_load_ushort v204, v[140:141], off offset:64
	global_load_ushort v98, v[142:143], off offset:64
	global_load_ushort v205, v[144:145], off offset:64
	global_load_ushort v99, v[146:147], off offset:64
	global_load_ushort v206, v[132:133], off offset:96
	global_load_ushort v100, v[134:135], off offset:96
	global_load_ushort v207, v[136:137], off offset:96
	global_load_ushort v101, v[138:139], off offset:96
	global_load_ushort v208, v[140:141], off offset:96
	global_load_ushort v102, v[142:143], off offset:96
	global_load_ushort v209, v[144:145], off offset:96
	global_load_ushort v103, v[146:147], off offset:96
	global_load_ushort v210, v[132:133], off offset:128
	global_load_ushort v104, v[134:135], off offset:128
	global_load_ushort v211, v[136:137], off offset:128
	global_load_ushort v105, v[138:139], off offset:128
	global_load_ushort v212, v[140:141], off offset:128
	global_load_ushort v106, v[142:143], off offset:128
	global_load_ushort v213, v[144:145], off offset:128
	global_load_ushort v107, v[146:147], off offset:128
	global_load_ushort v214, v[132:133], off offset:160
	global_load_ushort v108, v[134:135], off offset:160
	global_load_ushort v215, v[136:137], off offset:160
	global_load_ushort v109, v[138:139], off offset:160
	global_load_ushort v216, v[140:141], off offset:160
	global_load_ushort v110, v[142:143], off offset:160
	global_load_ushort v217, v[144:145], off offset:160
	global_load_ushort v111, v[146:147], off offset:160
	global_load_ushort v218, v[132:133], off offset:192
	global_load_ushort v112, v[134:135], off offset:192
	global_load_ushort v219, v[136:137], off offset:192
	global_load_ushort v113, v[138:139], off offset:192
	global_load_ushort v220, v[140:141], off offset:192
	global_load_ushort v114, v[142:143], off offset:192
	global_load_ushort v221, v[144:145], off offset:192
	global_load_ushort v115, v[146:147], off offset:192
	global_load_ushort v222, v[132:133], off offset:224
	global_load_ushort v116, v[134:135], off offset:224
	global_load_ushort v223, v[136:137], off offset:224
	global_load_ushort v117, v[138:139], off offset:224
	global_load_ushort v224, v[140:141], off offset:224
	global_load_ushort v118, v[142:143], off offset:224
	global_load_ushort v225, v[144:145], off offset:224
	global_load_ushort v119, v[146:147], off offset:224
	s_waitcnt vmcnt(63)
	v_mfma_f32_16x16x32_bf16 v[148:151], v[0:3], v[56:59], 0
	v_mfma_f32_16x16x32_bf16 v[152:155], v[0:3], v[60:63], 0
	v_mfma_f32_16x16x32_bf16 v[156:159], v[0:3], v[64:67], 0
	v_mfma_f32_16x16x32_bf16 v[160:163], v[0:3], v[68:71], 0
	v_mfma_f32_16x16x32_bf16 v[164:167], v[0:3], v[72:75], 0
	v_mfma_f32_16x16x32_bf16 v[168:171], v[0:3], v[76:79], 0
	v_mfma_f32_16x16x32_bf16 v[172:175], v[0:3], v[80:83], 0
	v_mfma_f32_16x16x32_bf16 v[176:179], v[0:3], v[84:87], 0
	s_waitcnt vmcnt(56)
	v_add_f32_e32 v148, v43, v148
	v_add_f32_e32 v149, v43, v149
	v_add_f32_e32 v150, v43, v150
	v_add_f32_e32 v151, v43, v151
	v_mul_f32_e32 v148, 0xbfb8aa3b, v148
	v_mul_f32_e32 v149, 0xbfb8aa3b, v149
	v_mul_f32_e32 v150, 0xbfb8aa3b, v150
	v_mul_f32_e32 v151, 0xbfb8aa3b, v151
	v_exp_f32_e32 v148, v148
	v_exp_f32_e32 v149, v149
	v_exp_f32_e32 v150, v150
	v_exp_f32_e32 v151, v151
	v_lshlrev_b32_e32 v194, 16, v194
	v_lshlrev_b32_e32 v195, 16, v195
	v_lshlrev_b32_e32 v196, 16, v196
	v_lshlrev_b32_e32 v197, 16, v197
	v_add_f32_e32 v148, 1.0, v148
	v_add_f32_e32 v149, 1.0, v149
	v_add_f32_e32 v150, 1.0, v150
	v_add_f32_e32 v151, 1.0, v151
	v_rcp_f32_e32 v148, v148
	v_rcp_f32_e32 v149, v149
	v_rcp_f32_e32 v150, v150
	v_rcp_f32_e32 v151, v151
	v_lshlrev_b32_e32 v88, 16, v88
	v_lshlrev_b32_e32 v89, 16, v89
	v_lshlrev_b32_e32 v90, 16, v90
	v_lshlrev_b32_e32 v91, 16, v91
	v_sub_f32_e32 v88, v88, v194
	v_sub_f32_e32 v89, v89, v195
	v_sub_f32_e32 v90, v90, v196
	v_sub_f32_e32 v91, v91, v197
	v_fmac_f32_e32 v194, v148, v88
	v_fmac_f32_e32 v195, v149, v89
	v_fmac_f32_e32 v196, v150, v90
	v_fmac_f32_e32 v197, v151, v91
	v_cvt_pk_bf16_f32 v194, v194, s0
	v_cvt_pk_bf16_f32 v195, v195, s0
	v_cvt_pk_bf16_f32 v196, v196, s0
	v_cvt_pk_bf16_f32 v197, v197, s0
	global_store_short v[132:133], v194, off
	global_store_short v[136:137], v195, off
	global_store_short v[140:141], v196, off
	global_store_short v[144:145], v197, off
	s_waitcnt vmcnt(52)
	v_add_f32_e32 v152, v44, v152
	v_add_f32_e32 v153, v44, v153
	v_add_f32_e32 v154, v44, v154
	v_add_f32_e32 v155, v44, v155
	v_mul_f32_e32 v152, 0xbfb8aa3b, v152
	v_mul_f32_e32 v153, 0xbfb8aa3b, v153
	v_mul_f32_e32 v154, 0xbfb8aa3b, v154
	v_mul_f32_e32 v155, 0xbfb8aa3b, v155
	v_exp_f32_e32 v152, v152
	v_exp_f32_e32 v153, v153
	v_exp_f32_e32 v154, v154
	v_exp_f32_e32 v155, v155
	v_lshlrev_b32_e32 v198, 16, v198
	v_lshlrev_b32_e32 v199, 16, v199
	v_lshlrev_b32_e32 v200, 16, v200
	v_lshlrev_b32_e32 v201, 16, v201
	v_add_f32_e32 v152, 1.0, v152
	v_add_f32_e32 v153, 1.0, v153
	v_add_f32_e32 v154, 1.0, v154
	v_add_f32_e32 v155, 1.0, v155
	v_rcp_f32_e32 v152, v152
	v_rcp_f32_e32 v153, v153
	v_rcp_f32_e32 v154, v154
	v_rcp_f32_e32 v155, v155
	v_lshlrev_b32_e32 v92, 16, v92
	v_lshlrev_b32_e32 v93, 16, v93
	v_lshlrev_b32_e32 v94, 16, v94
	v_lshlrev_b32_e32 v95, 16, v95
	v_sub_f32_e32 v92, v92, v198
	v_sub_f32_e32 v93, v93, v199
	v_sub_f32_e32 v94, v94, v200
	v_sub_f32_e32 v95, v95, v201
	v_fmac_f32_e32 v198, v152, v92
	v_fmac_f32_e32 v199, v153, v93
	v_fmac_f32_e32 v200, v154, v94
	v_fmac_f32_e32 v201, v155, v95
	v_cvt_pk_bf16_f32 v198, v198, s0
	v_cvt_pk_bf16_f32 v199, v199, s0
	v_cvt_pk_bf16_f32 v200, v200, s0
	v_cvt_pk_bf16_f32 v201, v201, s0
	global_store_short v[132:133], v198, off offset:32
	global_store_short v[136:137], v199, off offset:32
	global_store_short v[140:141], v200, off offset:32
	global_store_short v[144:145], v201, off offset:32
	s_waitcnt vmcnt(48)
; __device__ __forceinline__ float b2f(u16 b) { return __uint_as_float(((unsigned)b) << 16); }
; __device__ __forceinline__ float sigmoidf_(float x) { return __builtin_amdgcn_rcpf(1.f + __builtin_amdgcn_exp2f(-1.4426950408889634f * x)); }
; __device__ __forceinline__ void vmix_phase(u16* V, const u16* VF, const u16* vmid, const u16* v2T, const float* v0) {
;     ...
;       _Pragma("unroll") for (int j = 0; j < 4; ++j) {
;         size_t idx = (size_t)(tok0 + fq * 4 + j) * CM + ch;
;         float v = b2f(V[idx]), vf = b2f(VF[idx]);
;         V[idx] = f2b(v + (vf - v) * sigmoidf_(v0c + acc[j]));
;       }
	v_add_f32_e32 v156, v45, v156
	v_add_f32_e32 v157, v45, v157
	v_add_f32_e32 v158, v45, v158
	v_add_f32_e32 v159, v45, v159
	v_mul_f32_e32 v156, 0xbfb8aa3b, v156
	v_mul_f32_e32 v157, 0xbfb8aa3b, v157
	v_mul_f32_e32 v158, 0xbfb8aa3b, v158
	v_mul_f32_e32 v159, 0xbfb8aa3b, v159
	v_exp_f32_e32 v156, v156
	v_exp_f32_e32 v157, v157
	v_exp_f32_e32 v158, v158
	v_exp_f32_e32 v159, v159
	v_lshlrev_b32_e32 v202, 16, v202
	v_lshlrev_b32_e32 v203, 16, v203
	v_lshlrev_b32_e32 v204, 16, v204
	v_lshlrev_b32_e32 v205, 16, v205
	v_add_f32_e32 v156, 1.0, v156
	v_add_f32_e32 v157, 1.0, v157
	v_add_f32_e32 v158, 1.0, v158
	v_add_f32_e32 v159, 1.0, v159
	v_rcp_f32_e32 v156, v156
	v_rcp_f32_e32 v157, v157
	v_rcp_f32_e32 v158, v158
	v_rcp_f32_e32 v159, v159
	v_lshlrev_b32_e32 v96, 16, v96
	v_lshlrev_b32_e32 v97, 16, v97
	v_lshlrev_b32_e32 v98, 16, v98
	v_lshlrev_b32_e32 v99, 16, v99
	v_sub_f32_e32 v96, v96, v202
	v_sub_f32_e32 v97, v97, v203
	v_sub_f32_e32 v98, v98, v204
	v_sub_f32_e32 v99, v99, v205
	v_fmac_f32_e32 v202, v156, v96
	v_fmac_f32_e32 v203, v157, v97
	v_fmac_f32_e32 v204, v158, v98
	v_fmac_f32_e32 v205, v159, v99
	v_cvt_pk_bf16_f32 v202, v202, s0
	v_cvt_pk_bf16_f32 v203, v203, s0
	v_cvt_pk_bf16_f32 v204, v204, s0
	v_cvt_pk_bf16_f32 v205, v205, s0
	global_store_short v[132:133], v202, off offset:64
	global_store_short v[136:137], v203, off offset:64
	global_store_short v[140:141], v204, off offset:64
	global_store_short v[144:145], v205, off offset:64
	s_waitcnt vmcnt(44)
	v_add_f32_e32 v160, v46, v160
	v_add_f32_e32 v161, v46, v161
	v_add_f32_e32 v162, v46, v162
	v_add_f32_e32 v163, v46, v163
	v_mul_f32_e32 v160, 0xbfb8aa3b, v160
	v_mul_f32_e32 v161, 0xbfb8aa3b, v161
	v_mul_f32_e32 v162, 0xbfb8aa3b, v162
	v_mul_f32_e32 v163, 0xbfb8aa3b, v163
	v_exp_f32_e32 v160, v160
	v_exp_f32_e32 v161, v161
	v_exp_f32_e32 v162, v162
	v_exp_f32_e32 v163, v163
	v_lshlrev_b32_e32 v206, 16, v206
	v_lshlrev_b32_e32 v207, 16, v207
	v_lshlrev_b32_e32 v208, 16, v208
	v_lshlrev_b32_e32 v209, 16, v209
	v_add_f32_e32 v160, 1.0, v160
	v_add_f32_e32 v161, 1.0, v161
	v_add_f32_e32 v162, 1.0, v162
	v_add_f32_e32 v163, 1.0, v163
	v_rcp_f32_e32 v160, v160
	v_rcp_f32_e32 v161, v161
	v_rcp_f32_e32 v162, v162
	v_rcp_f32_e32 v163, v163
	v_lshlrev_b32_e32 v100, 16, v100
	v_lshlrev_b32_e32 v101, 16, v101
	v_lshlrev_b32_e32 v102, 16, v102
	v_lshlrev_b32_e32 v103, 16, v103
	v_sub_f32_e32 v100, v100, v206
	v_sub_f32_e32 v101, v101, v207
	v_sub_f32_e32 v102, v102, v208
	v_sub_f32_e32 v103, v103, v209
	v_fmac_f32_e32 v206, v160, v100
	v_fmac_f32_e32 v207, v161, v101
	v_fmac_f32_e32 v208, v162, v102
	v_fmac_f32_e32 v209, v163, v103
	v_cvt_pk_bf16_f32 v206, v206, s0
	v_cvt_pk_bf16_f32 v207, v207, s0
	v_cvt_pk_bf16_f32 v208, v208, s0
	v_cvt_pk_bf16_f32 v209, v209, s0
	global_store_short v[132:133], v206, off offset:96
	global_store_short v[136:137], v207, off offset:96
	global_store_short v[140:141], v208, off offset:96
	global_store_short v[144:145], v209, off offset:96
	s_waitcnt vmcnt(40)
	v_add_f32_e32 v164, v47, v164
	v_add_f32_e32 v165, v47, v165
	v_add_f32_e32 v166, v47, v166
	v_add_f32_e32 v167, v47, v167
	v_mul_f32_e32 v164, 0xbfb8aa3b, v164
	v_mul_f32_e32 v165, 0xbfb8aa3b, v165
	v_mul_f32_e32 v166, 0xbfb8aa3b, v166
	v_mul_f32_e32 v167, 0xbfb8aa3b, v167
	v_exp_f32_e32 v164, v164
	v_exp_f32_e32 v165, v165
	v_exp_f32_e32 v166, v166
	v_exp_f32_e32 v167, v167
	v_lshlrev_b32_e32 v210, 16, v210
	v_lshlrev_b32_e32 v211, 16, v211
	v_lshlrev_b32_e32 v212, 16, v212
	v_lshlrev_b32_e32 v213, 16, v213
	v_add_f32_e32 v164, 1.0, v164
	v_add_f32_e32 v165, 1.0, v165
	v_add_f32_e32 v166, 1.0, v166
	v_add_f32_e32 v167, 1.0, v167
	v_rcp_f32_e32 v164, v164
	v_rcp_f32_e32 v165, v165
	v_rcp_f32_e32 v166, v166
	v_rcp_f32_e32 v167, v167
	v_lshlrev_b32_e32 v104, 16, v104
	v_lshlrev_b32_e32 v105, 16, v105
	v_lshlrev_b32_e32 v106, 16, v106
	v_lshlrev_b32_e32 v107, 16, v107
	v_sub_f32_e32 v104, v104, v210
	v_sub_f32_e32 v105, v105, v211
	v_sub_f32_e32 v106, v106, v212
	v_sub_f32_e32 v107, v107, v213
	v_fmac_f32_e32 v210, v164, v104
	v_fmac_f32_e32 v211, v165, v105
	v_fmac_f32_e32 v212, v166, v106
	v_fmac_f32_e32 v213, v167, v107
	v_cvt_pk_bf16_f32 v210, v210, s0
	v_cvt_pk_bf16_f32 v211, v211, s0
	v_cvt_pk_bf16_f32 v212, v212, s0
	v_cvt_pk_bf16_f32 v213, v213, s0
	global_store_short v[132:133], v210, off offset:128
	global_store_short v[136:137], v211, off offset:128
	global_store_short v[140:141], v212, off offset:128
	global_store_short v[144:145], v213, off offset:128
	s_waitcnt vmcnt(36)
; __device__ __forceinline__ float b2f(u16 b) { return __uint_as_float(((unsigned)b) << 16); }
; __device__ __forceinline__ float sigmoidf_(float x) { return __builtin_amdgcn_rcpf(1.f + __builtin_amdgcn_exp2f(-1.4426950408889634f * x)); }
; #define MFMA16(a, b, c) __builtin_amdgcn_mfma_f32_16x16x32_bf16(a, b, c, 0, 0, 0)
; __device__ __forceinline__ void vmix_phase(u16* V, const u16* VF, const u16* vmid, const u16* v2T, const float* v0) {
;     ...
;   for (int it = blockIdx.x; it < NTOK / 16; it += gridDim.x) {
;     int tok0 = it * 16;
;     bf16x8 a = ld8(vmid + (size_t)(tok0 + fr) * 32 + fq * 8);
;     _Pragma("unroll") for (int n = 0; n < 8; ++n) {
;       int ch = wv * 128 + n * 16 + fr;
;       bf16x8 b = ld8(v2T + (size_t)ch * 32 + fq * 8);
;       f32x4 acc = {0.f, 0.f, 0.f, 0.f};
;       acc = MFMA16(a, b, acc);
;       float v0c = v0[ch];
;       _Pragma("unroll") for (int j = 0; j < 4; ++j) {
;         size_t idx = (size_t)(tok0 + fq * 4 + j) * CM + ch;
;         float v = b2f(V[idx]), vf = b2f(VF[idx]);
;         V[idx] = f2b(v + (vf - v) * sigmoidf_(v0c + acc[j]));
;       }
	v_add_f32_e32 v168, v48, v168
	v_add_f32_e32 v169, v48, v169
	v_add_f32_e32 v170, v48, v170
	v_add_f32_e32 v171, v48, v171
	v_mul_f32_e32 v168, 0xbfb8aa3b, v168
	v_mul_f32_e32 v169, 0xbfb8aa3b, v169
	v_mul_f32_e32 v170, 0xbfb8aa3b, v170
	v_mul_f32_e32 v171, 0xbfb8aa3b, v171
	v_exp_f32_e32 v168, v168
	v_exp_f32_e32 v169, v169
	v_exp_f32_e32 v170, v170
	v_exp_f32_e32 v171, v171
	v_lshlrev_b32_e32 v214, 16, v214
	v_lshlrev_b32_e32 v215, 16, v215
	v_lshlrev_b32_e32 v216, 16, v216
	v_lshlrev_b32_e32 v217, 16, v217
	v_add_f32_e32 v168, 1.0, v168
	v_add_f32_e32 v169, 1.0, v169
	v_add_f32_e32 v170, 1.0, v170
	v_add_f32_e32 v171, 1.0, v171
	v_rcp_f32_e32 v168, v168
	v_rcp_f32_e32 v169, v169
	v_rcp_f32_e32 v170, v170
	v_rcp_f32_e32 v171, v171
	v_lshlrev_b32_e32 v108, 16, v108
	v_lshlrev_b32_e32 v109, 16, v109
	v_lshlrev_b32_e32 v110, 16, v110
	v_lshlrev_b32_e32 v111, 16, v111
	v_sub_f32_e32 v108, v108, v214
	v_sub_f32_e32 v109, v109, v215
	v_sub_f32_e32 v110, v110, v216
	v_sub_f32_e32 v111, v111, v217
	v_fmac_f32_e32 v214, v168, v108
	v_fmac_f32_e32 v215, v169, v109
	v_fmac_f32_e32 v216, v170, v110
	v_fmac_f32_e32 v217, v171, v111
	v_cvt_pk_bf16_f32 v214, v214, s0
	v_cvt_pk_bf16_f32 v215, v215, s0
	v_cvt_pk_bf16_f32 v216, v216, s0
	v_cvt_pk_bf16_f32 v217, v217, s0
	global_store_short v[132:133], v214, off offset:160
	global_store_short v[136:137], v215, off offset:160
	global_store_short v[140:141], v216, off offset:160
	global_store_short v[144:145], v217, off offset:160
	s_waitcnt vmcnt(32)
	v_add_f32_e32 v172, v49, v172
	v_add_f32_e32 v173, v49, v173
	v_add_f32_e32 v174, v49, v174
	v_add_f32_e32 v175, v49, v175
	v_mul_f32_e32 v172, 0xbfb8aa3b, v172
	v_mul_f32_e32 v173, 0xbfb8aa3b, v173
	v_mul_f32_e32 v174, 0xbfb8aa3b, v174
	v_mul_f32_e32 v175, 0xbfb8aa3b, v175
	v_exp_f32_e32 v172, v172
	v_exp_f32_e32 v173, v173
	v_exp_f32_e32 v174, v174
	v_exp_f32_e32 v175, v175
	v_lshlrev_b32_e32 v218, 16, v218
	v_lshlrev_b32_e32 v219, 16, v219
	v_lshlrev_b32_e32 v220, 16, v220
	v_lshlrev_b32_e32 v221, 16, v221
	v_add_f32_e32 v172, 1.0, v172
	v_add_f32_e32 v173, 1.0, v173
	v_add_f32_e32 v174, 1.0, v174
	v_add_f32_e32 v175, 1.0, v175
	v_rcp_f32_e32 v172, v172
	v_rcp_f32_e32 v173, v173
	v_rcp_f32_e32 v174, v174
	v_rcp_f32_e32 v175, v175
	v_lshlrev_b32_e32 v112, 16, v112
	v_lshlrev_b32_e32 v113, 16, v113
	v_lshlrev_b32_e32 v114, 16, v114
	v_lshlrev_b32_e32 v115, 16, v115
	v_sub_f32_e32 v112, v112, v218
	v_sub_f32_e32 v113, v113, v219
	v_sub_f32_e32 v114, v114, v220
	v_sub_f32_e32 v115, v115, v221
	v_fmac_f32_e32 v218, v172, v112
	v_fmac_f32_e32 v219, v173, v113
	v_fmac_f32_e32 v220, v174, v114
	v_fmac_f32_e32 v221, v175, v115
	v_cvt_pk_bf16_f32 v218, v218, s0
	v_cvt_pk_bf16_f32 v219, v219, s0
	v_cvt_pk_bf16_f32 v220, v220, s0
	v_cvt_pk_bf16_f32 v221, v221, s0
	global_store_short v[132:133], v218, off offset:192
	global_store_short v[136:137], v219, off offset:192
	global_store_short v[140:141], v220, off offset:192
	global_store_short v[144:145], v221, off offset:192
	s_waitcnt vmcnt(28)
	v_add_f32_e32 v176, v50, v176
	v_add_f32_e32 v177, v50, v177
	v_add_f32_e32 v178, v50, v178
	v_add_f32_e32 v179, v50, v179
	v_mul_f32_e32 v176, 0xbfb8aa3b, v176
	v_mul_f32_e32 v177, 0xbfb8aa3b, v177
	v_mul_f32_e32 v178, 0xbfb8aa3b, v178
	v_mul_f32_e32 v179, 0xbfb8aa3b, v179
	v_exp_f32_e32 v176, v176
	v_exp_f32_e32 v177, v177
	v_exp_f32_e32 v178, v178
	v_exp_f32_e32 v179, v179
	v_lshlrev_b32_e32 v222, 16, v222
	v_lshlrev_b32_e32 v223, 16, v223
	v_lshlrev_b32_e32 v224, 16, v224
	v_lshlrev_b32_e32 v225, 16, v225
	v_add_f32_e32 v176, 1.0, v176
	v_add_f32_e32 v177, 1.0, v177
	v_add_f32_e32 v178, 1.0, v178
	v_add_f32_e32 v179, 1.0, v179
	v_rcp_f32_e32 v176, v176
	v_rcp_f32_e32 v177, v177
	v_rcp_f32_e32 v178, v178
	v_rcp_f32_e32 v179, v179
	v_lshlrev_b32_e32 v116, 16, v116
	v_lshlrev_b32_e32 v117, 16, v117
	v_lshlrev_b32_e32 v118, 16, v118
	v_lshlrev_b32_e32 v119, 16, v119
	v_sub_f32_e32 v116, v116, v222
	v_sub_f32_e32 v117, v117, v223
	v_sub_f32_e32 v118, v118, v224
	v_sub_f32_e32 v119, v119, v225
	v_fmac_f32_e32 v222, v176, v116
	v_fmac_f32_e32 v223, v177, v117
	v_fmac_f32_e32 v224, v178, v118
	v_fmac_f32_e32 v225, v179, v119
	v_cvt_pk_bf16_f32 v222, v222, s0
	v_cvt_pk_bf16_f32 v223, v223, s0
	v_cvt_pk_bf16_f32 v224, v224, s0
	v_cvt_pk_bf16_f32 v225, v225, s0
	global_store_short v[132:133], v222, off offset:224
	global_store_short v[136:137], v223, off offset:224
	global_store_short v[140:141], v224, off offset:224
	global_store_short v[144:145], v225, off offset:224
	s_add_i32 s0, s0, s10
	s_cmpk_lt_i32 s1, 0x1800
	s_cbranch_scc1 .LBB0_2641
